# up+resid epilogue coalescing + two norm vmcnt(0) waits removed
# speedup vs baseline: 1.0289x; 1.0112x over previous
.LBB0_304:
	v_mbcnt_lo_u32_b32 v223, -1, 0
	v_mbcnt_hi_u32_b32 v223, -1, v223
	v_and_b32_e32 v224, 3, v223
	v_lshrrev_b32_e32 v223, 2, v223
	v_lshl_or_b32 v222, v224, 4, v223
	v_lshlrev_b32_e32 v222, 2, v222
	ds_bpermute_b32 v6, v222, v6
	ds_bpermute_b32 v7, v222, v7
	ds_bpermute_b32 v8, v222, v8
	ds_bpermute_b32 v9, v222, v9
	ds_bpermute_b32 v10, v222, v10
	ds_bpermute_b32 v11, v222, v11
	ds_bpermute_b32 v12, v222, v12
	ds_bpermute_b32 v13, v222, v13
	ds_bpermute_b32 v14, v222, v14
	ds_bpermute_b32 v15, v222, v15
	ds_bpermute_b32 v16, v222, v16
	ds_bpermute_b32 v17, v222, v17
	ds_bpermute_b32 v18, v222, v18
	ds_bpermute_b32 v19, v222, v19
	ds_bpermute_b32 v20, v222, v20
	ds_bpermute_b32 v21, v222, v21
	s_waitcnt lgkmcnt(8)
	ds_bpermute_b32 v22, v222, v22
	ds_bpermute_b32 v23, v222, v23
	ds_bpermute_b32 v24, v222, v24
	ds_bpermute_b32 v25, v222, v25
	ds_bpermute_b32 v26, v222, v26
	ds_bpermute_b32 v27, v222, v27
	ds_bpermute_b32 v28, v222, v28
	ds_bpermute_b32 v29, v222, v29
	s_waitcnt lgkmcnt(8)
	ds_bpermute_b32 v30, v222, v30
	ds_bpermute_b32 v31, v222, v31
	ds_bpermute_b32 v32, v222, v32
	ds_bpermute_b32 v33, v222, v33
	ds_bpermute_b32 v34, v222, v34
	ds_bpermute_b32 v35, v222, v35
	ds_bpermute_b32 v36, v222, v36
	ds_bpermute_b32 v37, v222, v37
	s_waitcnt lgkmcnt(8)
	ds_bpermute_b32 v38, v222, v38
	ds_bpermute_b32 v39, v222, v39
	ds_bpermute_b32 v40, v222, v40
	ds_bpermute_b32 v41, v222, v41
	ds_bpermute_b32 v42, v222, v42
	ds_bpermute_b32 v43, v222, v43
	ds_bpermute_b32 v44, v222, v44
	ds_bpermute_b32 v45, v222, v45
	s_waitcnt lgkmcnt(8)
	ds_bpermute_b32 v46, v222, v46
	ds_bpermute_b32 v47, v222, v47
	ds_bpermute_b32 v48, v222, v48
	ds_bpermute_b32 v49, v222, v49
	ds_bpermute_b32 v50, v222, v50
	ds_bpermute_b32 v51, v222, v51
	ds_bpermute_b32 v52, v222, v52
	ds_bpermute_b32 v53, v222, v53
	s_waitcnt lgkmcnt(8)
	ds_bpermute_b32 v54, v222, v54
	ds_bpermute_b32 v55, v222, v55
	ds_bpermute_b32 v56, v222, v56
	ds_bpermute_b32 v57, v222, v57
	ds_bpermute_b32 v58, v222, v58
	ds_bpermute_b32 v59, v222, v59
	ds_bpermute_b32 v60, v222, v60
	ds_bpermute_b32 v61, v222, v61
	s_waitcnt lgkmcnt(8)
	ds_bpermute_b32 v62, v222, v62
	ds_bpermute_b32 v63, v222, v63
	ds_bpermute_b32 v64, v222, v64
	ds_bpermute_b32 v65, v222, v65
	ds_bpermute_b32 v66, v222, v66
	ds_bpermute_b32 v67, v222, v67
	ds_bpermute_b32 v68, v222, v68
	ds_bpermute_b32 v69, v222, v69
	s_waitcnt lgkmcnt(8)
	ds_bpermute_b32 v70, v222, v70
	ds_bpermute_b32 v71, v222, v71
	ds_bpermute_b32 v72, v222, v72
	ds_bpermute_b32 v73, v222, v73
	ds_bpermute_b32 v74, v222, v74
	ds_bpermute_b32 v75, v222, v75
	ds_bpermute_b32 v76, v222, v76
	ds_bpermute_b32 v77, v222, v77
	s_waitcnt lgkmcnt(8)
	ds_bpermute_b32 v78, v222, v78
	ds_bpermute_b32 v79, v222, v79
	ds_bpermute_b32 v80, v222, v80
	ds_bpermute_b32 v81, v222, v81
	ds_bpermute_b32 v82, v222, v82
	ds_bpermute_b32 v83, v222, v83
	ds_bpermute_b32 v84, v222, v84
	ds_bpermute_b32 v85, v222, v85
	s_waitcnt lgkmcnt(8)
	ds_bpermute_b32 v86, v222, v86
	ds_bpermute_b32 v87, v222, v87
	ds_bpermute_b32 v88, v222, v88
	ds_bpermute_b32 v89, v222, v89
	ds_bpermute_b32 v90, v222, v90
	ds_bpermute_b32 v91, v222, v91
	ds_bpermute_b32 v92, v222, v92
	ds_bpermute_b32 v93, v222, v93
	s_waitcnt lgkmcnt(8)
	ds_bpermute_b32 v94, v222, v94
	ds_bpermute_b32 v95, v222, v95
	ds_bpermute_b32 v96, v222, v96
	ds_bpermute_b32 v97, v222, v97
	ds_bpermute_b32 v98, v222, v98
	ds_bpermute_b32 v99, v222, v99
	ds_bpermute_b32 v100, v222, v100
	ds_bpermute_b32 v101, v222, v101
	s_waitcnt lgkmcnt(8)
	ds_bpermute_b32 v102, v222, v102
	ds_bpermute_b32 v103, v222, v103
	ds_bpermute_b32 v104, v222, v104
	ds_bpermute_b32 v105, v222, v105
	ds_bpermute_b32 v106, v222, v106
	ds_bpermute_b32 v107, v222, v107
	ds_bpermute_b32 v108, v222, v108
	ds_bpermute_b32 v109, v222, v109
	s_waitcnt lgkmcnt(8)
	ds_bpermute_b32 v110, v222, v110
	ds_bpermute_b32 v111, v222, v111
	ds_bpermute_b32 v112, v222, v112
	ds_bpermute_b32 v113, v222, v113
	ds_bpermute_b32 v114, v222, v114
	ds_bpermute_b32 v115, v222, v115
	ds_bpermute_b32 v116, v222, v116
	ds_bpermute_b32 v117, v222, v117
	s_waitcnt lgkmcnt(8)
	ds_bpermute_b32 v118, v222, v118
	ds_bpermute_b32 v119, v222, v119
	ds_bpermute_b32 v120, v222, v120
	ds_bpermute_b32 v121, v222, v121
	ds_bpermute_b32 v122, v222, v122
	ds_bpermute_b32 v123, v222, v123
	ds_bpermute_b32 v124, v222, v124
	ds_bpermute_b32 v125, v222, v125
	s_waitcnt lgkmcnt(8)
	ds_bpermute_b32 v126, v222, v126
	ds_bpermute_b32 v127, v222, v127
	ds_bpermute_b32 v128, v222, v128
	ds_bpermute_b32 v129, v222, v129
	ds_bpermute_b32 v130, v222, v130
	ds_bpermute_b32 v131, v222, v131
	ds_bpermute_b32 v132, v222, v132
	ds_bpermute_b32 v133, v222, v133
	s_waitcnt lgkmcnt(8)
	v_and_b32_e32 v225, 0x60, v208
	v_lshl_or_b32 v225, v224, 2, v225
	s_lshl_b32 s25, s76, 8
	s_add_i32 s38, s25, s62
	v_or_b32_e32 v192, s38, v223
	v_lshl_or_b32 v194, s77, 8, v225
	s_waitcnt lgkmcnt(0)
	s_mov_b64 s[36:37], -1
	s_andn2_b64 vcc, exec, s[34:35]
	v_ashrrev_i32_e32 v195, 31, v194
	v_or_b32_e32 v190, 16, v192
	v_or_b32_e32 v188, 32, v192
	v_or_b32_e32 v186, 48, v192
	s_cbranch_vccz .LBB0_307
	s_andn2_b64 vcc, exec, s[36:37]
	s_cbranch_vccz .LBB0_308

.LBB0_581:
	s_ashr_i32 s27, s26, 31
	s_lshl_b64 s[26:27], s[26:27], 12
	s_waitcnt lgkmcnt(0)
	s_add_u32 s2, s2, s26
	s_addc_u32 s3, s3, s27
	global_load_dwordx4 v[66:69], v0, s[2:3]
	global_load_dwordx4 v[62:65], v0, s[2:3] offset:1024
	global_load_dwordx4 v[58:61], v0, s[2:3] offset:2048
	global_load_dwordx4 v[54:57], v0, s[2:3] offset:3072
	v_cndmask_b32_e64 v70, 0, 1, s[74:75]
	v_cmp_ne_u32_e64 s[2:3], 1, v70
	s_andn2_b64 vcc, exec, s[74:75]
	s_cbranch_vccz .LBB0_584
	s_and_b64 vcc, exec, s[4:5]
	s_mov_b64 s[4:5], -1
	s_cbranch_vccz .LBB0_585

.LBB0_614:
	s_ashr_i32 s15, s14, 31
	s_lshl_b64 s[24:25], s[14:15], 12
	s_waitcnt lgkmcnt(0)
	s_add_u32 s4, s4, s24
	s_addc_u32 s5, s5, s25
	global_load_dwordx4 v[46:49], v0, s[4:5]
	global_load_dwordx4 v[42:45], v0, s[4:5] offset:1024
	global_load_dwordx4 v[38:41], v0, s[4:5] offset:2048
	global_load_dwordx4 v[34:37], v0, s[4:5] offset:3072
	s_and_b64 vcc, exec, s[2:3]
	s_cbranch_vccnz .LBB0_616
	s_ashr_i32 s4, s14, 13
	s_mul_hi_i32 s5, s4, 0x18000
	s_mul_i32 s4, s4, 0x18000
	s_add_u32 s4, s21, s4
	s_addc_u32 s5, s22, s5
	s_add_u32 s24, s4, 0x1000
	s_addc_u32 s25, s5, 0
	v_lshlrev_b32_e32 v54, 4, v5
	v_lshlrev_b32_e32 v86, 4, v220
	v_lshlrev_b32_e32 v87, 4, v221
	global_load_dwordx4 v[22:25], v0, s[4:5]
	global_load_dwordx4 v[26:29], v0, s[4:5] offset:1024
	global_load_dwordx4 v[74:77], v0, s[24:25]
	global_load_dwordx4 v[70:73], v54, s[24:25]
	s_nop 0
	global_load_dwordx4 v[54:57], v0, s[4:5] offset:2048
	global_load_dwordx4 v[58:61], v0, s[4:5] offset:3072
	global_load_dwordx4 v[90:93], v86, s[24:25]
	s_nop 0
	global_load_dwordx4 v[86:89], v87, s[24:25]
